# adds nt on scan output stores and FFT input loads; drops the store-order-dependent scan wait edit
# speedup vs baseline: 1.0295x; 1.0006x over previous
; #define LAS __attribute__((address_space(3)))
; __device__ __forceinline__ void unpack8(const v4u u, float (&f)[8]) { f[0] = bf2f(u.x & 0xffffu); f[1] = bf2f(u.x >> 16); f[2] = bf2f(u.y & 0xffffu); f[3] = bf2f(u.y >> 16); f[4] = bf2f(u.z & 0xffffu); f[5] = bf2f(u.z >> 16); f[6] = bf2f(u.w & 0xffffu); f[7] = bf2f(u.w >> 16); }
; template <int LOGN, int NCOL>
; __device__ __forceinline__ void fft_items(const Args& a, LAS unsigned char* lds, const WCtx& w, const bf16* VT, float* FO, int rowbase0, float scale) {
;     ...
;     for (int it = w.bid; it < 16 * NCG; it += w.G) {
;         const int b = it / NCG, cg = it - b * NCG, ch = cg * NCOL + c;
;         const bf16* src = VT + (size_t)(b * 256 + ch) * (2 * N);
;         for (int m = j; m < N / 8; m += TPC) {
;             const v4u vr = *(const v4u*)(src + 8 * m), vi = *(const v4u*)(src + N + 8 * m); float f[8];
;             unpack8(vr, f); *(LAS f32x4*)(XR + c * CS + fpad(8 * m)) = (f32x4){f[0], f[1], f[2], f[3]}; *(LAS f32x4*)(XR + c * CS + fpad(8 * m) + 4) = (f32x4){f[4], f[5], f[6], f[7]};
;             unpack8(vi, f); *(LAS f32x4*)(XI + c * CS + fpad(8 * m)) = (f32x4){f[0], f[1], f[2], f[3]}; *(LAS f32x4*)(XI + c * CS + fpad(8 * m) + 4) = (f32x4){f[4], f[5], f[6], f[7]}; }
.LBB0_1003:
	v_ashrrev_i32_e32 v29, 31, v28
	v_lshlrev_b64 v[48:49], 1, v[28:29]
	v_lshl_add_u64 v[44:45], v[24:25], 0, v[48:49]
	global_load_dwordx4 v[44:47], v[44:45], off nt
	v_lshl_add_u64 v[48:49], v[26:27], 0, v[48:49]
	global_load_dwordx4 v[52:55], v[48:49], off nt
	v_lshlrev_b32_e32 v29, 1, v31
	v_and_b32_e32 v29, 0xffffffe0, v29
	v_add_u32_e32 v29, v30, v29
	v_add_u32_e32 v43, 0xfffef000, v29
	s_movk_i32 s4, 0xbf
	v_cmp_lt_i32_e64 s[4:5], s4, v31
	v_add_u32_e32 v30, 0x800, v30
	v_add_u32_e32 v28, 0x200, v28
	s_or_b64 s[6:7], s[4:5], s[6:7]
	s_waitcnt vmcnt(1)
	v_lshlrev_b32_e32 v56, 16, v44
	v_and_b32_e32 v57, 0xffff0000, v44
	v_lshlrev_b32_e32 v58, 16, v45
	v_and_b32_e32 v59, 0xffff0000, v45
	v_lshlrev_b32_e32 v44, 16, v46
	v_and_b32_e32 v45, 0xffff0000, v46
	v_lshlrev_b32_e32 v46, 16, v47
	v_and_b32_e32 v47, 0xffff0000, v47
	ds_write_b128 v43, v[56:59]
	v_add_u32_e32 v43, 0xfffef010, v29
	ds_write_b128 v43, v[44:47]
	s_waitcnt vmcnt(0)
	v_lshlrev_b32_e32 v44, 16, v52
	v_and_b32_e32 v45, 0xffff0000, v52
	v_lshlrev_b32_e32 v46, 16, v53
	v_and_b32_e32 v47, 0xffff0000, v53
	v_lshlrev_b32_e32 v52, 16, v54
	v_and_b32_e32 v53, 0xffff0000, v54
	v_lshlrev_b32_e32 v54, 16, v55
	v_and_b32_e32 v55, 0xffff0000, v55
	ds_write_b128 v29, v[44:47]
	ds_write_b128 v29, v[52:55] offset:16
	v_add_u32_e32 v29, 64, v31
	v_mov_b32_e32 v31, v29
	s_andn2_b64 exec, exec, s[6:7]
	s_cbranch_execnz .LBB0_1003

; #define LAS __attribute__((address_space(3)))
; __device__ __forceinline__ void unpack8(const v4u u, float (&f)[8]) { f[0] = bf2f(u.x & 0xffffu); f[1] = bf2f(u.x >> 16); f[2] = bf2f(u.y & 0xffffu); f[3] = bf2f(u.y >> 16); f[4] = bf2f(u.z & 0xffffu); f[5] = bf2f(u.z >> 16); f[6] = bf2f(u.w & 0xffffu); f[7] = bf2f(u.w >> 16); }
; template <int LOGN, int NCOL>
; __device__ __forceinline__ void fft_items(const Args& a, LAS unsigned char* lds, const WCtx& w, const bf16* VT, float* FO, int rowbase0, float scale) {
;     ...
;         const bf16* src = VT + (size_t)(b * 256 + ch) * (2 * N);
;         for (int m = j; m < N / 8; m += TPC) {
;             const v4u vr = *(const v4u*)(src + 8 * m), vi = *(const v4u*)(src + N + 8 * m); float f[8];
;             unpack8(vr, f); *(LAS f32x4*)(XR + c * CS + fpad(8 * m)) = (f32x4){f[0], f[1], f[2], f[3]}; *(LAS f32x4*)(XR + c * CS + fpad(8 * m) + 4) = (f32x4){f[4], f[5], f[6], f[7]};
;             unpack8(vi, f); *(LAS f32x4*)(XI + c * CS + fpad(8 * m)) = (f32x4){f[0], f[1], f[2], f[3]}; *(LAS f32x4*)(XI + c * CS + fpad(8 * m) + 4) = (f32x4){f[4], f[5], f[6], f[7]}; }
.LBB0_1026:
	v_ashrrev_i32_e32 v5, 31, v4
	v_lshl_add_u64 v[12:13], v[4:5], 1, v[2:3]
	global_load_dwordx4 v[8:11], v[12:13], off nt
	s_nop 0
	global_load_dwordx4 v[12:15], v[12:13], off offset:512 nt
	v_lshlrev_b32_e32 v5, 1, v7
	v_and_b32_e32 v5, 0xffffffe0, v5
	v_add_u32_e32 v5, v6, v5
	v_cmp_lt_i32_e64 s[4:5], 15, v7
	v_add_u32_e32 v4, 0x80, v4
	v_add_u32_e32 v6, 0x200, v6
	s_or_b64 s[6:7], s[4:5], s[6:7]
	s_waitcnt vmcnt(0)
	v_lshlrev_b32_e32 v16, 16, v8
	v_and_b32_e32 v17, 0xffff0000, v8
	v_lshlrev_b32_e32 v18, 16, v9
	v_and_b32_e32 v19, 0xffff0000, v9
	v_lshlrev_b32_e32 v8, 16, v10
	v_and_b32_e32 v9, 0xffff0000, v10
	v_lshlrev_b32_e32 v10, 16, v11
	v_and_b32_e32 v11, 0xffff0000, v11
	ds_write_b128 v5, v[16:19]
	ds_write_b128 v5, v[8:11] offset:16
	v_lshlrev_b32_e32 v8, 16, v12
	v_and_b32_e32 v9, 0xffff0000, v12
	v_lshlrev_b32_e32 v10, 16, v13
	v_and_b32_e32 v11, 0xffff0000, v13
	v_lshlrev_b32_e32 v12, 16, v14
	v_and_b32_e32 v13, 0xffff0000, v14
	v_lshlrev_b32_e32 v14, 16, v15
	v_and_b32_e32 v15, 0xffff0000, v15
	ds_write_b128 v5, v[8:11] offset:34816
	ds_write_b128 v5, v[12:15] offset:34832
	v_add_u32_e32 v5, 16, v7
	v_mov_b32_e32 v7, v5
	s_andn2_b64 exec, exec, s[6:7]
	s_cbranch_execnz .LBB0_1026

; #define LAS __attribute__((address_space(3)))
; __device__ __forceinline__ bf16 bfr(float x) { return (bf16)cvt_pk_bf16(x, x); }
; __device__ __forceinline__ void st4bf(LAS bf16* p, float a, float b, float c, float d) { v2u w; w.x = cvt_pk_bf16(a, b); w.y = cvt_pk_bf16(c, d); *(LAS v2u*)p = w; }
; #define LBAR() asm volatile("s_waitcnt lgkmcnt(0)\n\ts_barrier" ::: "memory")
; __device__ __forceinline__ void phase_scan_chunk(const Args& a, LAS unsigned char* lds, const WCtx& w, int l) {
;     ...
;                 { f32x16 acc = zero16();
;                   if (wn >= wm) { const LAS bf16* Ap = (wm == 0 && wn == 0) ? TX + 32 * TS : TK + 32 * wm * TS; const LAS bf16* Bp = (wn == 0) ? TQ : TX;
;                       acc = mma64(acc, Ap, Bp, lane); }
;                   const int i = 32 * wn + r;
; #pragma unroll
;                   for (int q = 0; q < 4; ++q) { const int j0 = 32 * wm + 8 * q + 4 * hh;
;                       st4bf(TP + i * TS + j0, (j0 <= i) ? acc[4 * q] : 0.f, (j0 + 1 <= i) ? acc[4 * q + 1] : 0.f, (j0 + 2 <= i) ? acc[4 * q + 2] : 0.f, (j0 + 3 <= i) ? acc[4 * q + 3] : 0.f); } }
;                 LBAR();
;                 { bf16* sop = so + (size_t)chain_row(b, dir, c, 32 * wm + 4 * hh) * 256; const long sstep = dir ? -256 : 256;
;                   f32x16 o = zero16(); o = mma64s<false, true>(o, TP, wm, TVT, wn, lane); o = mma64(o, TQ + 32 * wm * TS, TST + 32 * wn * TS, lane);
;                   f32x16 ds = zero16(); ds = mma64s<true, true>(ds, TKD, wm, TVT, wn, lane);
; #pragma unroll
;                   for (int q = 0; q < 4; ++q) { const f32x4 dv = *(const LAS f32x4*)(DEC + 32 * wm + 8 * q + 4 * hh);
; #pragma unroll
;                       for (int t = 0; t < 4; ++t) { S[4 * q + t] = dv[t] * S[4 * q + t] + ds[4 * q + t]; sop[(long)(8 * q + t) * sstep] = bfr(o[4 * q + t]); } } }
.LBB0_1432:
	s_nop 10
	v_cndmask_b32_e64 v2, v2, 0, s[46:47]
	v_cndmask_b32_e64 v3, 0, v3, s[48:49]
	v_cvt_pk_bf16_f32 v2, v2, v3
	v_cndmask_b32_e64 v4, v4, 0, s[50:51]
	v_cndmask_b32_e64 v5, v5, 0, s[52:53]
	v_cvt_pk_bf16_f32 v3, v4, v5
	ds_write_b64 v167, v[2:3] offset:55296
	v_cndmask_b32_e64 v2, v6, 0, s[54:55]
	v_cndmask_b32_e64 v3, 0, v7, s[56:57]
	v_cvt_pk_bf16_f32 v2, v2, v3
	v_cndmask_b32_e64 v4, v8, 0, s[58:59]
	v_cndmask_b32_e64 v5, v9, 0, s[60:61]
	v_cvt_pk_bf16_f32 v3, v4, v5
	ds_write_b64 v167, v[2:3] offset:55312
	v_cndmask_b32_e64 v2, v10, 0, s[62:63]
	v_cndmask_b32_e64 v3, 0, v11, s[64:65]
	v_cvt_pk_bf16_f32 v2, v2, v3
	s_cmp_lt_u32 s30, 4
	v_cndmask_b32_e64 v4, v12, 0, s[66:67]
	v_cndmask_b32_e64 v5, v13, 0, s[68:69]
	v_cvt_pk_bf16_f32 v3, v4, v5
	ds_write_b64 v167, v[2:3] offset:55328
	v_cndmask_b32_e64 v2, v14, 0, s[70:71]
	s_cselect_b64 vcc, -1, 0
	v_cndmask_b32_e64 v3, 0, v15, s[72:73]
	v_cvt_pk_bf16_f32 v2, v2, v3
	s_and_b64 s[2:3], vcc, exec
	v_cndmask_b32_e64 v4, v16, 0, s[74:75]
	v_cndmask_b32_e64 v5, v17, 0, s[76:77]
	v_cvt_pk_bf16_f32 v3, v4, v5
	ds_write_b64 v167, v[2:3] offset:55344
	v_cndmask_b32_e32 v2, v157, v123, vcc
	s_cselect_b32 s2, 0xff, s39
	v_add_u32_e32 v3, s29, v2
	v_sub_u32_e32 v2, s2, v2
	v_add_u32_e32 v2, s28, v2
	s_cselect_b32 s3, s26, s27
	v_cndmask_b32_e64 v2, v2, v3, s[0:1]
	v_add_u32_e32 v2, s3, v2
	v_ashrrev_i32_e32 v3, 31, v2
	v_lshlrev_b64 v[2:3], 9, v[2:3]
	s_waitcnt lgkmcnt(0)
	s_barrier
	v_lshl_add_u64 v[80:81], v[58:59], 0, v[2:3]
	v_add_u32_e32 v2, v128, v97
	ds_read_b128 v[2:5], v2 offset:55296
	v_add_u32_e32 v6, v125, v83
	ds_read_b128 v[18:21], v6 offset:36864
	v_add_u32_e32 v22, v128, v96
	ds_read_b128 v[22:25], v22 offset:55296
	s_waitcnt lgkmcnt(1)
	v_mfma_f32_32x32x16_bf16 v[2:17], v[2:5], v[18:21], 0
	v_add_u32_e32 v26, v125, v84
	ds_read_b128 v[34:37], v26 offset:36864
	v_add_u32_e32 v26, v125, v85
	ds_read_b128 v[220:223], v26 offset:36864
	v_add_u32_e32 v26, v125, v86
	ds_read_b128 v[242:245], v26 offset:36864
	v_add_u32_e32 v219, v128, v89
	s_waitcnt lgkmcnt(2)
	v_mfma_f32_32x32x16_bf16 v[2:17], v[22:25], v[34:37], v[2:17]
	v_add_u32_e32 v22, v128, v95
	ds_read_b128 v[22:25], v22 offset:55296
	s_add_i32 s29, s29, 64
	s_sub_i32 s28, s28, 64
	s_add_i32 s30, s30, 1
	s_cmpk_eq_i32 s29, 0x900
	s_waitcnt lgkmcnt(0)
	v_mfma_f32_32x32x16_bf16 v[2:17], v[22:25], v[220:223], v[2:17]
	v_add_u32_e32 v22, v128, v94
	ds_read_b128 v[22:25], v22 offset:55296
	s_waitcnt lgkmcnt(0)
	v_mfma_f32_32x32x16_bf16 v[2:17], v[22:25], v[242:245], v[2:17]
	ds_read_b128 v[22:25], v129
	ds_read_b128 v[26:29], v129 offset:32
	ds_read_b128 v[30:33], v130 offset:46080
	ds_read_b128 v[246:249], v130 offset:46112
	s_waitcnt lgkmcnt(1)
	v_mfma_f32_32x32x16_bf16 v[2:17], v[22:25], v[30:33], v[2:17]
	s_waitcnt lgkmcnt(0)
	v_mfma_f32_32x32x16_bf16 v[2:17], v[26:29], v[246:249], v[2:17]
	ds_read_b128 v[22:25], v129 offset:64
	ds_read_b128 v[26:29], v130 offset:46144
	s_waitcnt lgkmcnt(0)
	v_mfma_f32_32x32x16_bf16 v[2:17], v[22:25], v[26:29], v[2:17]
	ds_read_b128 v[22:25], v129 offset:96
	ds_read_b128 v[26:29], v130 offset:46176
	ds_read_b128 v[246:249], v219 offset:27648
	s_waitcnt lgkmcnt(1)
	v_mfma_f32_32x32x16_bf16 v[2:17], v[22:25], v[26:29], v[2:17]
	v_add_u32_e32 v22, v128, v88
	ds_read_b128 v[22:25], v22 offset:27648
	s_waitcnt lgkmcnt(0)
	v_mfma_f32_32x32x16_bf16 v[18:33], v[22:25], v[18:21], 0
	v_mfma_f32_32x32x16_bf16 v[18:33], v[246:249], v[34:37], v[18:33]
	v_add_u32_e32 v34, v128, v91
	ds_read_b128 v[34:37], v34 offset:27648
	s_waitcnt lgkmcnt(0)
	v_mfma_f32_32x32x16_bf16 v[18:33], v[34:37], v[220:223], v[18:33]
	v_add_u32_e32 v34, v128, v92
	ds_read_b128 v[34:37], v34 offset:27648
	s_waitcnt lgkmcnt(0)
	v_mfma_f32_32x32x16_bf16 v[18:33], v[34:37], v[242:245], v[18:33]
	ds_read_b128 v[34:37], v131 offset:65024
	v_cvt_pk_bf16_f32 v2, v2, v2
	global_store_short v[80:81], v2, off nt
	v_cvt_pk_bf16_f32 v219, v3, v3
	v_lshl_add_u64 v[2:3], v[52:53], 1, v[80:81]
	global_store_short v[2:3], v219, off nt
	v_cvt_pk_bf16_f32 v4, v4, v4
	v_lshl_add_u64 v[2:3], v[2:3], 0, v[54:55]
	global_store_short v[2:3], v4, off nt
	v_cvt_pk_bf16_f32 v4, v5, v5
	v_lshl_add_u64 v[80:81], v[2:3], 0, v[54:55]
	global_store_short v[80:81], v4, off nt
	ds_read_b128 v[2:5], v131 offset:65056
	v_cvt_pk_bf16_f32 v6, v6, v6
	v_lshl_add_u64 v[80:81], v[80:81], 0, v[56:57]
	global_store_short v[80:81], v6, off nt
	v_cvt_pk_bf16_f32 v219, v7, v7
	v_lshl_add_u64 v[6:7], v[80:81], 0, v[54:55]
	global_store_short v[6:7], v219, off nt
	v_cvt_pk_bf16_f32 v8, v8, v8
	v_lshl_add_u64 v[6:7], v[6:7], 0, v[54:55]
	global_store_short v[6:7], v8, off nt
	v_cvt_pk_bf16_f32 v8, v9, v9
	v_lshl_add_u64 v[80:81], v[6:7], 0, v[54:55]
	global_store_short v[80:81], v8, off nt
	ds_read_b128 v[6:9], v131 offset:65088
	v_cvt_pk_bf16_f32 v10, v10, v10
	v_lshl_add_u64 v[80:81], v[80:81], 0, v[56:57]
	global_store_short v[80:81], v10, off nt
	v_cvt_pk_bf16_f32 v219, v11, v11
	v_lshl_add_u64 v[10:11], v[80:81], 0, v[54:55]
	global_store_short v[10:11], v219, off nt
	v_cvt_pk_bf16_f32 v12, v12, v12
	v_lshl_add_u64 v[10:11], v[10:11], 0, v[54:55]
	global_store_short v[10:11], v12, off nt
	v_cvt_pk_bf16_f32 v12, v13, v13
	v_lshl_add_u64 v[80:81], v[10:11], 0, v[54:55]
	global_store_short v[80:81], v12, off nt
	ds_read_b128 v[10:13], v131 offset:65120
	v_cvt_pk_bf16_f32 v14, v14, v14
	v_lshl_add_u64 v[80:81], v[80:81], 0, v[56:57]
	global_store_short v[80:81], v14, off nt
	v_cvt_pk_bf16_f32 v219, v15, v15
	v_lshl_add_u64 v[14:15], v[80:81], 0, v[54:55]
	global_store_short v[14:15], v219, off nt
	v_lshl_add_u64 v[14:15], v[14:15], 0, v[54:55]
	s_waitcnt lgkmcnt(2)
	v_pk_fma_f32 v[68:69], v[68:69], v[2:3], v[22:23]
	v_lshl_add_u64 v[2:3], v[14:15], 0, v[54:55]
	v_cvt_pk_bf16_f32 v16, v16, v16
	global_store_short v[14:15], v16, off nt
	v_pk_fma_f32 v[70:71], v[70:71], v[4:5], v[24:25]
	v_cvt_pk_bf16_f32 v4, v17, v17
	global_store_short v[2:3], v4, off nt
	s_waitcnt lgkmcnt(0)
	s_barrier
	s_waitcnt lgkmcnt(0)
	v_pk_fma_f32 v[78:79], v[78:79], v[12:13], v[32:33]
	v_pk_fma_f32 v[76:77], v[76:77], v[10:11], v[30:31]
	v_pk_fma_f32 v[74:75], v[74:75], v[8:9], v[28:29]
	v_pk_fma_f32 v[72:73], v[72:73], v[6:7], v[26:27]
	v_pk_fma_f32 v[66:67], v[66:67], v[36:37], v[20:21]
	v_pk_fma_f32 v[64:65], v[64:65], v[34:35], v[18:19]
	s_cbranch_scc1 .LBB0_1430

; #define LAS __attribute__((address_space(3)))
; __device__ __forceinline__ bf16 bfr(float x) { return (bf16)cvt_pk_bf16(x, x); }
; __device__ __forceinline__ void phase_scan_chunk(const Args& a, LAS unsigned char* lds, const WCtx& w, int l) {
;     ...
;                 { bf16* sop = so + (size_t)chain_row(b, dir, c, 32 * wm + 4 * hh) * 256; const long sstep = dir ? -256 : 256;
;                   f32x16 o = zero16(); o = mma64s<false, true>(o, TP, wm, TVT, wn, lane);
;                   f32x16 qs = zero16(); qs = mma64(qs, TQ + 32 * wm * TS, TST + 32 * wn * TS, lane);
;                   f32x16 ds = zero16(); ds = mma64s<true, true>(ds, TKD, wm, TVT, wn, lane);
;                   const float dsc = EG[63];
; #pragma unroll
;                   for (int q = 0; q < 4; ++q) { const f32x4 eg = *(const LAS f32x4*)(EG + 32 * wm + 8 * q + 4 * hh);
; #pragma unroll
;                       for (int t = 0; t < 4; ++t) { S[4 * q + t] = dsc * S[4 * q + t] + ds[4 * q + t]; sop[(long)(8 * q + t) * sstep] = bfr(o[4 * q + t] + eg[t] * qs[4 * q + t]); } } }
.LBB0_1535:
	v_cndmask_b32_e64 v2, v222, v221, s[0:1]
	v_add_u32_e32 v2, s23, v2
	v_ashrrev_i32_e32 v3, 31, v2
	s_waitcnt lgkmcnt(0)
	s_barrier
	v_lshlrev_b64 v[2:3], 9, v[2:3]
	v_lshl_add_u64 v[158:159], v[136:137], 0, v[2:3]
	ds_read_b128 v[2:5], v197 offset:55296
	ds_read_b128 v[34:37], v200 offset:36864
	ds_read_b128 v[18:21], v201 offset:55296
	ds_read_b128 v[220:223], v202 offset:36864
	s_mov_b64 s[2:3], 0x4000
	s_waitcnt lgkmcnt(2)
	v_mfma_f32_32x32x16_bf16 v[2:17], v[2:5], v[34:37], 0
	s_add_i32 s34, s34, 2
	s_addk_i32 s30, 0x80
	v_lshl_add_u64 v[138:139], v[138:139], 0, s[2:3]
	s_addk_i32 s35, 0xff80
	s_andn2_b64 vcc, exec, s[88:89]
	s_waitcnt lgkmcnt(0)
	v_mfma_f32_32x32x16_bf16 v[2:17], v[18:21], v[220:223], v[2:17]
	ds_read_b128 v[18:21], v203 offset:55296
	ds_read_b128 v[224:227], v204 offset:36864
	s_waitcnt lgkmcnt(0)
	v_mfma_f32_32x32x16_bf16 v[2:17], v[18:21], v[224:227], v[2:17]
	ds_read_b128 v[18:21], v205 offset:55296
	ds_read_b128 v[238:241], v206 offset:36864
	s_waitcnt lgkmcnt(0)
	v_mfma_f32_32x32x16_bf16 v[2:17], v[18:21], v[238:241], v[2:17]
	ds_read_b128 v[18:21], v174
	ds_read_b128 v[38:41], v174 offset:32
	ds_read_b128 v[22:25], v175 offset:46080
	ds_read_b128 v[42:45], v175 offset:46112
	s_waitcnt lgkmcnt(1)
	v_mfma_f32_32x32x16_bf16 v[18:33], v[18:21], v[22:25], 0
	s_waitcnt lgkmcnt(0)
	v_mfma_f32_32x32x16_bf16 v[18:33], v[38:41], v[42:45], v[18:33]
	ds_read_b128 v[38:41], v174 offset:64
	ds_read_b128 v[42:45], v175 offset:46144
	s_waitcnt lgkmcnt(0)
	v_mfma_f32_32x32x16_bf16 v[18:33], v[38:41], v[42:45], v[18:33]
	ds_read_b128 v[38:41], v174 offset:96
	ds_read_b128 v[42:45], v175 offset:46176
	ds_read_b128 v[242:245], v208 offset:27648
	s_waitcnt lgkmcnt(1)
	v_mfma_f32_32x32x16_bf16 v[18:33], v[38:41], v[42:45], v[18:33]
	ds_read_b128 v[38:41], v207 offset:27648
	s_waitcnt lgkmcnt(0)
	v_mfma_f32_32x32x16_bf16 v[34:49], v[38:41], v[34:37], 0
	v_mfma_f32_32x32x16_bf16 v[34:49], v[242:245], v[220:223], v[34:49]
	ds_read_b128 v[220:223], v209 offset:27648
	s_waitcnt lgkmcnt(0)
	v_mfma_f32_32x32x16_bf16 v[34:49], v[220:223], v[224:227], v[34:49]
	ds_read_b128 v[220:223], v210 offset:27648
	s_waitcnt lgkmcnt(0)
	v_mfma_f32_32x32x16_bf16 v[34:49], v[220:223], v[238:241], v[34:49]
	ds_read_b32 v156, v161 offset:65020
	ds_read_b128 v[220:223], v177 offset:64768
	s_waitcnt lgkmcnt(0)
	v_fma_f32 v2, v18, v220, v2
	v_cvt_pk_bf16_f32 v2, v2, v2
	global_store_short v[158:159], v2, off nt
	v_fma_f32 v2, v19, v221, v3
	v_cvt_pk_bf16_f32 v18, v2, v2
	v_lshl_add_u64 v[2:3], v[128:129], 1, v[158:159]
	v_fma_f32 v4, v20, v222, v4
	global_store_short v[2:3], v18, off nt
	v_cvt_pk_bf16_f32 v4, v4, v4
	v_lshl_add_u64 v[2:3], v[2:3], 0, v[130:131]
	global_store_short v[2:3], v4, off nt
	v_fma_f32 v4, v21, v223, v5
	v_cvt_pk_bf16_f32 v4, v4, v4
	v_lshl_add_u64 v[18:19], v[2:3], 0, v[130:131]
	global_store_short v[18:19], v4, off nt
	ds_read_b128 v[2:5], v177 offset:64800
	v_lshl_add_u64 v[18:19], v[18:19], 0, v[132:133]
	v_pk_fma_f32 v[142:143], v[142:143], v[156:157], v[48:49] op_sel_hi:[1,0,1]
	v_pk_fma_f32 v[144:145], v[144:145], v[156:157], v[46:47] op_sel_hi:[1,0,1]
	v_pk_fma_f32 v[146:147], v[146:147], v[156:157], v[44:45] op_sel_hi:[1,0,1]
	s_waitcnt lgkmcnt(0)
	v_fma_f32 v2, v22, v2, v6
	v_cvt_pk_bf16_f32 v2, v2, v2
	global_store_short v[18:19], v2, off nt
	v_fma_f32 v2, v23, v3, v7
	v_cvt_pk_bf16_f32 v6, v2, v2
	v_lshl_add_u64 v[2:3], v[18:19], 0, v[130:131]
	v_fma_f32 v4, v24, v4, v8
	global_store_short v[2:3], v6, off nt
	v_cvt_pk_bf16_f32 v4, v4, v4
	v_lshl_add_u64 v[2:3], v[2:3], 0, v[130:131]
	global_store_short v[2:3], v4, off nt
	v_fma_f32 v4, v25, v5, v9
	v_cvt_pk_bf16_f32 v4, v4, v4
	v_lshl_add_u64 v[6:7], v[2:3], 0, v[130:131]
	global_store_short v[6:7], v4, off nt
	ds_read_b128 v[2:5], v177 offset:64832
	v_lshl_add_u64 v[6:7], v[6:7], 0, v[132:133]
	v_pk_fma_f32 v[148:149], v[148:149], v[156:157], v[42:43] op_sel_hi:[1,0,1]
	v_pk_fma_f32 v[150:151], v[150:151], v[156:157], v[40:41] op_sel_hi:[1,0,1]
	v_pk_fma_f32 v[152:153], v[152:153], v[156:157], v[38:39] op_sel_hi:[1,0,1]
	s_waitcnt lgkmcnt(0)
	v_fma_f32 v2, v26, v2, v10
	v_cvt_pk_bf16_f32 v2, v2, v2
	global_store_short v[6:7], v2, off nt
	v_fma_f32 v2, v27, v3, v11
	v_cvt_pk_bf16_f32 v8, v2, v2
	v_lshl_add_u64 v[2:3], v[6:7], 0, v[130:131]
	v_fma_f32 v4, v28, v4, v12
	global_store_short v[2:3], v8, off nt
	v_cvt_pk_bf16_f32 v4, v4, v4
	v_lshl_add_u64 v[2:3], v[2:3], 0, v[130:131]
	global_store_short v[2:3], v4, off nt
	v_fma_f32 v4, v29, v5, v13
	v_cvt_pk_bf16_f32 v4, v4, v4
	v_lshl_add_u64 v[6:7], v[2:3], 0, v[130:131]
	global_store_short v[6:7], v4, off nt
	ds_read_b128 v[2:5], v177 offset:64864
	v_lshl_add_u64 v[6:7], v[6:7], 0, v[132:133]
	v_pk_fma_f32 v[154:155], v[154:155], v[156:157], v[36:37] op_sel_hi:[1,0,1]
	v_pk_fma_f32 v[140:141], v[140:141], v[156:157], v[34:35] op_sel_hi:[1,0,1]
	s_waitcnt lgkmcnt(0)
	v_fma_f32 v2, v30, v2, v14
	v_cvt_pk_bf16_f32 v2, v2, v2
	global_store_short v[6:7], v2, off nt
	v_fma_f32 v2, v31, v3, v15
	v_cvt_pk_bf16_f32 v8, v2, v2
	v_lshl_add_u64 v[2:3], v[6:7], 0, v[130:131]
	global_store_short v[2:3], v8, off nt
	v_fma_f32 v4, v32, v4, v16
	v_lshl_add_u64 v[2:3], v[2:3], 0, v[130:131]
	v_cvt_pk_bf16_f32 v4, v4, v4
	global_store_short v[2:3], v4, off nt
	v_lshl_add_u64 v[2:3], v[2:3], 0, v[130:131]
	v_fmac_f32_e32 v17, v33, v5
	v_cvt_pk_bf16_f32 v4, v17, v17
	global_store_short v[2:3], v4, off nt
	s_waitcnt lgkmcnt(0)
	s_barrier
	s_cbranch_vccz .LBB0_1509

; #define LAS __attribute__((address_space(3)))
; __device__ __forceinline__ bf16 bfr(float x) { return (bf16)cvt_pk_bf16(x, x); }
; __device__ __forceinline__ void phase_scan_chunk(const Args& a, LAS unsigned char* lds, const WCtx& w, int l) {
;     ...
;                 { bf16* sop = so + (size_t)chain_row(b, dir, c, 32 * wm + 4 * hh) * 256; const long sstep = dir ? -256 : 256;
;                   f32x16 o = zero16(); o = mma64s<false, true>(o, TP, wm, TVT, wn, lane);
;                   f32x16 qs = zero16(); qs = mma64(qs, TQ + 32 * wm * TS, TST + 32 * wn * TS, lane);
;                   f32x16 ds = zero16(); ds = mma64s<true, true>(ds, TKD, wm, TVT, wn, lane);
;                   const float dsc = EG[63];
; #pragma unroll
;                   for (int q = 0; q < 4; ++q) { const f32x4 eg = *(const LAS f32x4*)(EG + 32 * wm + 8 * q + 4 * hh);
; #pragma unroll
;                       for (int t = 0; t < 4; ++t) { S[4 * q + t] = dsc * S[4 * q + t] + ds[4 * q + t]; sop[(long)(8 * q + t) * sstep] = bfr(o[4 * q + t] + eg[t] * qs[4 * q + t]); } } }
.LBB0_1562:
	s_cmp_lt_u32 s34, 4
	s_cselect_b64 vcc, -1, 0
	s_and_b64 s[2:3], vcc, exec
	v_cndmask_b32_e32 v2, v157, v123, vcc
	s_cselect_b32 s2, 0xff, s39
	v_add_u32_e32 v221, s30, v2
	v_sub_u32_e32 v2, s2, v2
	v_add_u32_e32 v222, s35, v2
	v_subrev_u32_e32 v3, 64, v221
	v_add_u32_e32 v2, 64, v222
	s_cselect_b32 s23, s28, s29
	v_cndmask_b32_e64 v2, v2, v3, s[0:1]
	v_add_u32_e32 v2, s23, v2
	v_ashrrev_i32_e32 v3, 31, v2
	s_waitcnt lgkmcnt(0)
	s_barrier
	v_lshlrev_b64 v[2:3], 9, v[2:3]
	v_lshl_add_u64 v[158:159], v[136:137], 0, v[2:3]
	ds_read_b128 v[2:5], v197 offset:55296
	ds_read_b128 v[6:9], v200 offset:36864
	s_waitcnt lgkmcnt(0)
	v_mfma_f32_32x32x16_bf16 v[18:33], v[2:5], v[6:9], 0
	ds_read_b128 v[2:5], v201 offset:55296
	ds_read_b128 v[242:245], v202 offset:36864
	s_and_b64 vcc, exec, s[70:71]
	s_waitcnt lgkmcnt(0)
	v_mfma_f32_32x32x16_bf16 v[18:33], v[2:5], v[242:245], v[18:33]
	ds_read_b128 v[2:5], v203 offset:55296
	ds_read_b128 v[246:249], v204 offset:36864
	s_waitcnt lgkmcnt(0)
	v_mfma_f32_32x32x16_bf16 v[18:33], v[2:5], v[246:249], v[18:33]
	ds_read_b128 v[2:5], v205 offset:55296
	ds_read_b128 v[238:241], v206 offset:36864
	s_waitcnt lgkmcnt(0)
	v_mfma_f32_32x32x16_bf16 v[18:33], v[2:5], v[238:241], v[18:33]
	ds_read_b128 v[2:5], v174
	ds_read_b128 v[10:13], v174 offset:32
	ds_read_b128 v[14:17], v175 offset:46080
	ds_read_b128 v[224:227], v175 offset:46112
	s_waitcnt lgkmcnt(1)
	v_mfma_f32_32x32x16_bf16 v[34:49], v[2:5], v[14:17], 0
	s_waitcnt lgkmcnt(0)
	v_mfma_f32_32x32x16_bf16 v[34:49], v[10:13], v[224:227], v[34:49]
	ds_read_b128 v[2:5], v174 offset:64
	ds_read_b128 v[10:13], v175 offset:46144
	s_waitcnt lgkmcnt(0)
	v_mfma_f32_32x32x16_bf16 v[34:49], v[2:5], v[10:13], v[34:49]
	ds_read_b128 v[2:5], v174 offset:96
	ds_read_b128 v[10:13], v175 offset:46176
	ds_read_b128 v[224:227], v208 offset:27648
	s_waitcnt lgkmcnt(1)
	v_mfma_f32_32x32x16_bf16 v[34:49], v[2:5], v[10:13], v[34:49]
	ds_read_b128 v[2:5], v207 offset:27648
	s_waitcnt lgkmcnt(0)
	v_mfma_f32_32x32x16_bf16 v[2:17], v[2:5], v[6:9], 0
	v_mfma_f32_32x32x16_bf16 v[2:17], v[224:227], v[242:245], v[2:17]
	ds_read_b128 v[224:227], v209 offset:27648
	s_waitcnt lgkmcnt(0)
	v_mfma_f32_32x32x16_bf16 v[2:17], v[224:227], v[246:249], v[2:17]
	ds_read_b128 v[224:227], v210 offset:27648
	s_waitcnt lgkmcnt(0)
	v_mfma_f32_32x32x16_bf16 v[2:17], v[224:227], v[238:241], v[2:17]
	ds_read_b32 v156, v161 offset:65020
	ds_read_b128 v[224:227], v177 offset:64768
	s_waitcnt lgkmcnt(0)
	v_fma_f32 v18, v34, v224, v18
	v_cvt_pk_bf16_f32 v18, v18, v18
	global_store_short v[158:159], v18, off nt
	v_fma_f32 v18, v35, v225, v19
	v_cvt_pk_bf16_f32 v34, v18, v18
	v_lshl_add_u64 v[18:19], v[128:129], 1, v[158:159]
	v_fma_f32 v20, v36, v226, v20
	global_store_short v[18:19], v34, off nt
	v_cvt_pk_bf16_f32 v20, v20, v20
	v_lshl_add_u64 v[18:19], v[18:19], 0, v[130:131]
	global_store_short v[18:19], v20, off nt
	v_fma_f32 v20, v37, v227, v21
	v_cvt_pk_bf16_f32 v20, v20, v20
	v_lshl_add_u64 v[34:35], v[18:19], 0, v[130:131]
	global_store_short v[34:35], v20, off nt
	ds_read_b128 v[18:21], v177 offset:64800
	v_lshl_add_u64 v[34:35], v[34:35], 0, v[132:133]
	s_waitcnt lgkmcnt(0)
	v_fma_f32 v18, v38, v18, v22
	v_cvt_pk_bf16_f32 v18, v18, v18
	global_store_short v[34:35], v18, off nt
	v_fma_f32 v18, v39, v19, v23
	v_cvt_pk_bf16_f32 v22, v18, v18
	v_lshl_add_u64 v[18:19], v[34:35], 0, v[130:131]
	v_fma_f32 v20, v40, v20, v24
	global_store_short v[18:19], v22, off nt
	v_cvt_pk_bf16_f32 v20, v20, v20
	v_lshl_add_u64 v[18:19], v[18:19], 0, v[130:131]
	global_store_short v[18:19], v20, off nt
	v_fma_f32 v20, v41, v21, v25
	v_cvt_pk_bf16_f32 v20, v20, v20
	v_lshl_add_u64 v[22:23], v[18:19], 0, v[130:131]
	global_store_short v[22:23], v20, off nt
	ds_read_b128 v[18:21], v177 offset:64832
	v_lshl_add_u64 v[22:23], v[22:23], 0, v[132:133]
	s_waitcnt lgkmcnt(0)
	v_fma_f32 v18, v42, v18, v26
	v_cvt_pk_bf16_f32 v18, v18, v18
	global_store_short v[22:23], v18, off nt
	v_fma_f32 v18, v43, v19, v27
	v_cvt_pk_bf16_f32 v24, v18, v18
	v_lshl_add_u64 v[18:19], v[22:23], 0, v[130:131]
	v_fma_f32 v20, v44, v20, v28
	global_store_short v[18:19], v24, off nt
	v_cvt_pk_bf16_f32 v20, v20, v20
	v_lshl_add_u64 v[18:19], v[18:19], 0, v[130:131]
	global_store_short v[18:19], v20, off nt
	v_fma_f32 v20, v45, v21, v29
	v_cvt_pk_bf16_f32 v20, v20, v20
	v_lshl_add_u64 v[22:23], v[18:19], 0, v[130:131]
	global_store_short v[22:23], v20, off nt
	ds_read_b128 v[18:21], v177 offset:64864
	v_lshl_add_u64 v[22:23], v[22:23], 0, v[132:133]
	s_waitcnt lgkmcnt(0)
	v_fma_f32 v18, v46, v18, v30
	v_cvt_pk_bf16_f32 v18, v18, v18
	global_store_short v[22:23], v18, off nt
	v_fma_f32 v18, v47, v19, v31
	v_cvt_pk_bf16_f32 v24, v18, v18
	v_lshl_add_u64 v[18:19], v[22:23], 0, v[130:131]
	global_store_short v[18:19], v24, off nt
	v_fma_f32 v20, v48, v20, v32
	v_lshl_add_u64 v[18:19], v[18:19], 0, v[130:131]
	v_cvt_pk_bf16_f32 v20, v20, v20
	global_store_short v[18:19], v20, off nt
	v_lshl_add_u64 v[18:19], v[18:19], 0, v[130:131]
	v_fmac_f32_e32 v33, v49, v21
	v_cvt_pk_bf16_f32 v20, v33, v33
	global_store_short v[18:19], v20, off nt
	s_waitcnt lgkmcnt(0)
	s_barrier
; __device__ __forceinline__ float sigmoid_acc(float x) { return 1.0f / (1.0f + expf(-x)); }
; __device__ __forceinline__ float softplus_acc(float x) { return x > 20.f ? x : log1pf(expf(x)); }
; __device__ __forceinline__ void phase_scan_chunk(const Args& a, LAS unsigned char* lds, const WCtx& w, int l) {
;     ...
;                 if (gw4 == 0) { const float sp = softplus_acc(rs0s[u] + dtb); float g = -al * sp;
;                     g = wave_scan(g);
;                     G[lane] = g; EG[lane] = __expf(g); BD[lane] = (mix == 1) ? sigmoid_acc(rs1s[u]) : sp; }
	s_cbranch_vccnz .LBB0_1568
	s_waitcnt vmcnt(16)
	v_add_f32_e32 v18, v211, v214
	v_cmp_nlt_f32_e32 vcc, s10, v18
	s_and_saveexec_b64 s[2:3], vcc
	s_cbranch_execz .LBB0_1565
	v_mul_f32_e32 v19, 0x3fb8aa3b, v18
	v_rndne_f32_e32 v20, v19
	v_sub_f32_e32 v21, v19, v20
	v_fma_f32 v19, v18, s11, -v19
	v_fmac_f32_e32 v19, 0x32a5705f, v18
	v_add_f32_e32 v19, v21, v19
	v_cvt_i32_f32_e32 v20, v20
	v_exp_f32_e32 v19, v19
	v_cmp_ngt_f32_e32 vcc, s12, v18
	v_ldexp_f32 v19, v19, v20
	s_nop 0
	v_cndmask_b32_e32 v19, 0, v19, vcc
	v_cmp_nlt_f32_e32 vcc, s13, v18
	s_nop 1
	v_cndmask_b32_e32 v32, v235, v19, vcc
	v_add_f32_e32 v20, 1.0, v32
	v_add_f32_e32 v18, -1.0, v20
	v_sub_f32_e32 v19, v18, v20
	v_add_f32_e32 v19, 1.0, v19
	v_sub_f32_e32 v18, v32, v18
	v_add_f32_e32 v21, v18, v19
	v_frexp_mant_f32_e32 v22, v20
	v_cvt_f64_f32_e32 v[18:19], v20
	v_frexp_exp_i32_f64_e32 v18, v[18:19]
	v_cmp_gt_f32_e32 vcc, s14, v22
	s_nop 1
	v_subbrev_co_u32_e32 v26, vcc, 0, v18, vcc
	v_sub_u32_e32 v18, 0, v26
	v_ldexp_f32 v19, v20, v18
	v_add_f32_e32 v20, -1.0, v19
	v_add_f32_e32 v22, 1.0, v19
	v_ldexp_f32 v18, v21, v18
	v_add_f32_e32 v21, 1.0, v20
	v_add_f32_e32 v23, -1.0, v22
	v_sub_f32_e32 v21, v19, v21
	v_sub_f32_e32 v19, v19, v23
	v_add_f32_e32 v21, v18, v21
	v_add_f32_e32 v18, v18, v19
	v_add_f32_e32 v27, v22, v18
	v_rcp_f32_e32 v29, v27
	v_sub_f32_e32 v19, v22, v27
	v_add_f32_e32 v28, v18, v19
	v_add_f32_e32 v19, v20, v21
	v_mul_f32_e32 v31, v19, v29
	v_sub_f32_e32 v18, v20, v19
	v_mul_f32_e32 v20, v27, v31
	v_fma_f32 v22, v31, v27, -v20
	v_fmac_f32_e32 v22, v31, v28
	v_add_f32_e32 v30, v21, v18
	v_add_f32_e32 v18, v20, v22
	v_sub_f32_e32 v21, v19, v18
	v_pk_add_f32 v[24:25], v[18:19], v[20:21] neg_lo:[0,1] neg_hi:[0,1]
	v_mov_b32_e32 v23, v18
	v_pk_add_f32 v[18:19], v[24:25], v[22:23] neg_lo:[0,1] neg_hi:[0,1]
	v_cmp_neq_f32_e32 vcc, s22, v32
	v_add_f32_e32 v19, v30, v19
	v_add_f32_e32 v18, v18, v19
	v_add_f32_e32 v19, v21, v18
	v_mul_f32_e32 v30, v29, v19
	v_mul_f32_e32 v20, v27, v30
	v_fma_f32 v22, v30, v27, -v20
	v_fmac_f32_e32 v22, v30, v28
	v_sub_f32_e32 v21, v21, v19
	v_add_f32_e32 v27, v18, v21
	v_add_f32_e32 v18, v20, v22
	v_sub_f32_e32 v21, v19, v18
	v_pk_add_f32 v[24:25], v[18:19], v[20:21] neg_lo:[0,1] neg_hi:[0,1]
	v_mov_b32_e32 v23, v18
	v_pk_add_f32 v[18:19], v[24:25], v[22:23] neg_lo:[0,1] neg_hi:[0,1]
	s_nop 0
	v_add_f32_e32 v19, v27, v19
	v_add_f32_e32 v18, v18, v19
	v_add_f32_e32 v19, v31, v30
	v_add_f32_e32 v18, v21, v18
	v_sub_f32_e32 v20, v19, v31
	v_mul_f32_e32 v18, v29, v18
	v_sub_f32_e32 v20, v30, v20
	v_add_f32_e32 v20, v20, v18
	v_add_f32_e32 v22, v19, v20
	v_mul_f32_e32 v23, v22, v22
	v_fmamk_f32 v18, v23, 0x3e9b6dac, v250
	v_fmaak_f32 v199, v23, v18, 0x3f2aaada
	v_cvt_f32_i32_e32 v18, v26
	v_sub_f32_e32 v19, v22, v19
	v_sub_f32_e32 v19, v20, v19
	v_ldexp_f32 v24, v19, 1
	v_mul_f32_e32 v19, v22, v23
	v_ldexp_f32 v21, v22, 1
	v_pk_mul_f32 v[22:23], v[18:19], v[198:199]
	s_nop 0
	v_fma_f32 v20, v18, s15, -v22
	v_fmac_f32_e32 v20, 0xb102e308, v18
	v_pk_add_f32 v[18:19], v[22:23], v[20:21]
	s_nop 0
	v_sub_f32_e32 v21, v19, v21
	v_sub_f32_e32 v21, v23, v21
	v_add_f32_e32 v25, v24, v21
	v_mov_b32_e32 v24, v22
	v_pk_add_f32 v[22:23], v[18:19], v[22:23] neg_lo:[0,1] neg_hi:[0,1]
	v_pk_add_f32 v[26:27], v[18:19], v[24:25]
	v_mov_b32_e32 v21, v18
	v_mov_b32_e32 v23, v27
	v_pk_add_f32 v[28:29], v[20:21], v[22:23] neg_lo:[0,1] neg_hi:[0,1]
	v_pk_add_f32 v[20:21], v[20:21], v[22:23]
	v_mov_b32_e32 v24, v25
	v_pk_add_f32 v[22:23], v[20:21], v[18:19] op_sel:[1,0] op_sel_hi:[0,1] neg_lo:[0,1] neg_hi:[0,1]
	v_pk_add_f32 v[30:31], v[26:27], v[22:23] op_sel_hi:[1,0] neg_lo:[0,1] neg_hi:[0,1]
	v_mov_b32_e32 v26, v27
	v_mov_b32_e32 v27, v21
	v_pk_mov_b32 v[22:23], v[18:19], v[22:23] op_sel:[1,0]
	v_mov_b32_e32 v25, v18
	v_pk_add_f32 v[22:23], v[26:27], v[22:23] neg_lo:[0,1] neg_hi:[0,1]
	v_mov_b32_e32 v30, v28
	v_pk_add_f32 v[18:19], v[24:25], v[22:23] neg_lo:[0,1] neg_hi:[0,1]
	v_mov_b32_e32 v29, v21
	v_pk_add_f32 v[22:23], v[30:31], v[18:19]
	s_nop 0
	v_pk_add_f32 v[24:25], v[22:23], v[22:23] op_sel:[0,1] op_sel_hi:[1,0]
	s_nop 0
	v_pk_add_f32 v[20:21], v[20:21], v[24:25] op_sel:[1,0] op_sel_hi:[0,1]
	v_mov_b32_e32 v23, v20
	v_pk_add_f32 v[26:27], v[22:23], v[28:29] neg_lo:[0,1] neg_hi:[0,1]
	v_mov_b32_e32 v19, v24
	v_sub_f32_e32 v21, v22, v26
	v_pk_add_f32 v[18:19], v[18:19], v[26:27] neg_lo:[0,1] neg_hi:[0,1]
	v_sub_f32_e32 v21, v28, v21
	v_add_f32_e32 v18, v18, v21
	v_add_f32_e32 v18, v18, v19
	v_add_f32_e32 v18, v20, v18
	v_cndmask_b32_e32 v18, v235, v18, vcc
	v_cmp_lt_f32_e64 vcc, |v32|, s16
	s_nop 1
	v_cndmask_b32_e32 v18, v18, v32, vcc
